# baseline (speedup 1.0000x reference)
; #define PG8_STAGE(bufoff, gbase, voff) do { _Pragma("unroll") for (int _i = 0; _i < 2; ++_i) \
;         __builtin_amdgcn_global_load_lds((const unsigned*)((const char*)(gbase) + (voff)[_i]), (PG8_LAS unsigned*)(lds + (bufoff) + ldsw + _i * 8192), 16, 0, 0); } while (0)
; #define PG8_WAIT_V(n) asm volatile("s_waitcnt vmcnt(" #n ")" ::: "memory")
; #define PG8_BAR __builtin_amdgcn_s_barrier()
; template <class Epi, class Sched, bool ALIGN_EPI = false, bool SP2 = false>
; __device__ __forceinline__ void gemm_phase(PG8_LAS unsigned char* lds, const Gemm g, const Sched& S, const Epi& E) {
;     ...
;     const char* cA = (const char*)g.A + (size_t)cur.pm * tstep + (size_t)cur.kt0 * kstep; const char* cB = (const char*)g.Bt + (size_t)cur.pn * tstep + (size_t)cur.kt0 * kstep;
;     S.a_ready(cur);
;     if constexpr (SP2) {
;         PG8_STAGE(PG8_SB(0, 0), cB, voffB); PG8_STAGE(PG8_SB(0, 1), cB + hstep, voffB); PG8_STAGE(PG8_SA(0, 0), cA, voffA); PG8_STAGE(PG8_SA(0, 1), cA + hstep, voffA);
;         if (wr == 1) PG8_BAR;
;         PG8_WAIT_V(2); PG8_BAR;
;         PG8_STAGE(PG8_SB(1, 0), cB + kstep, voffB); PG8_STAGE(PG8_SA(1, 0), cA + kstep, voffA); PG8_STAGE(PG8_SB(1, 1), cB + hstep + kstep, voffB);
;         PG8_WAIT_V(6); PG8_BAR;
.LBB0_343:
	s_lshl_b32 s4, s19, 5
	s_xor_b64 s[26:27], s[26:27], -1
	s_lshl_b32 s33, s18, 13
	s_and_b32 s19, s4, 0x60
	s_add_u32 s70, s58, 0x1b800000
	s_mov_b64 s[44:45], 0x80
	s_addc_u32 s71, s59, 0
	s_add_i32 m0, s98, 0x18000
	v_lshl_add_u64 v[10:11], v[10:11], 0, s[44:45]
	s_waitcnt vmcnt(2)
	s_barrier
	global_load_lds_dwordx4 v[10:11], off
	v_lshl_add_u64 v[6:7], v[6:7], 0, s[44:45]
	s_add_i32 m0, s98, 0x1a000
	s_add_i32 s72, s98, 0x8000
	global_load_lds_dwordx4 v[6:7], off
	v_lshl_add_u64 v[6:7], v[8:9], 0, s[44:45]
	s_mov_b32 m0, s72
	s_add_i32 s73, s98, 0xa000
	global_load_lds_dwordx4 v[6:7], off
	v_lshl_add_u64 v[6:7], v[12:13], 0, s[44:45]
	s_mov_b32 m0, s73
	v_lshl_add_u64 v[4:5], v[4:5], 0, s[44:45]
	global_load_lds_dwordx4 v[6:7], off
	s_add_i32 m0, s98, 0x1c000
	v_lshl_add_u64 v[2:3], v[2:3], 0, s[44:45]
	global_load_lds_dwordx4 v[4:5], off
	s_add_i32 m0, s98, 0x1e000
	s_cmpk_lt_u32 s5, 0x100
	global_load_lds_dwordx4 v[2:3], off
	v_mul_f32_e32 v3, v16, v17
	v_trunc_f32_e32 v3, v3
	v_cvt_u32_f32_e32 v4, v3
	v_fma_f32 v3, -v3, v15, v16
	s_cselect_b64 s[28:29], -1, 0
	s_lshr_b32 s91, s79, s12
	s_lshr_b32 s75, s52, 3
	v_cmp_ge_f32_e64 s[4:5], |v3|, v15
	v_readfirstlane_b32 s12, v4
	s_cmp_lg_u64 s[4:5], 0
	s_addc_u32 s4, s12, 0
	s_and_b32 s76, s4, 0x7ff
	v_cvt_f32_u32_e32 v3, s76
	v_lshlrev_b32_e32 v4, 2, v197
	v_lshl_or_b32 v2, v197, 6, v198
	v_and_b32_e32 v4, 32, v4
	v_bitop3_b32 v4, v2, s33, v4 bitop3:0xde
	v_rcp_iflag_f32_e32 v2, v3
	v_rcp_iflag_f32_e32 v3, v18
	s_sub_i32 s4, 0, s76
	s_waitcnt vmcnt(6)
	v_mul_f32_e32 v2, 0x4f7ffffe, v2
	v_cvt_u32_f32_e32 v2, v2
	v_lshl_or_b32 v144, s18, 6, v197
	v_lshl_or_b32 v145, s19, 7, v199
	v_add_u32_e32 v242, 0x10000, v145
	v_or_b32_e32 v146, s19, v192
	v_readfirstlane_b32 s5, v2
	v_mul_f32_e32 v2, 0x4f7ffffe, v14
	v_cvt_u32_f32_e32 v2, v2
	s_mul_i32 s4, s4, s5
	s_mul_hi_u32 s4, s5, s4
	s_add_i32 s77, s5, s4
	v_readfirstlane_b32 s5, v2
	v_mul_f32_e32 v2, 0x4f7ffffe, v3
	v_cvt_u32_f32_e32 v2, v2
	s_sub_i32 s4, 0, s7
	s_mul_i32 s4, s4, s5
	s_mul_hi_u32 s4, s5, s4
	s_add_i32 s69, s5, s4
	s_sub_i32 s4, 0, s78
	v_readfirstlane_b32 s5, v2
	s_mul_i32 s4, s4, s5
	v_add_lshl_u32 v2, v200, v19, 1
	v_mov_b32_e32 v3, v1
	s_mul_hi_u32 s4, s5, s4
	v_lshl_add_u64 v[136:137], s[16:17], 0, v[2:3]
	v_add_lshl_u32 v2, v200, v20, 1
	s_mov_b32 s18, 0
	s_add_i32 s5, s5, s4
	v_lshl_add_u64 v[138:139], s[16:17], 0, v[2:3]
	v_add_u32_e32 v147, 0, v4
	s_barrier
	s_and_b64 vcc, exec, s[24:25]
	s_cbranch_vccz .Lprio_skip
	s_setprio 1
.Lprio_skip:
	s_branch .LBB0_346
.LBB0_344:
	s_mov_b64 s[30:31], 0

; #define PG8_STAGE(bufoff, gbase, voff) do { _Pragma("unroll") for (int _i = 0; _i < 2; ++_i) \
;         __builtin_amdgcn_global_load_lds((const unsigned*)((const char*)(gbase) + (voff)[_i]), (PG8_LAS unsigned*)(lds + (bufoff) + ldsw + _i * 8192), 16, 0, 0); } while (0)
; #define PG8_LDA(dst, b, h) do { _Pragma("unroll") for (int m = 0; m < 4; ++m) _Pragma("unroll") for (int k = 0; k < 2; ++k) dst[m][k] = *(const PG8_LAS bf16x8*)(lds + PG8_SA(b, h) + aoff + m * 2048 + k * 1024); } while (0)
; #define PG8_LDB(dst, b, h) do { _Pragma("unroll") for (int n = 0; n < 2; ++n) _Pragma("unroll") for (int k = 0; k < 2; ++k) dst[n][k] = *(const PG8_LAS bf16x8*)(lds + PG8_SB(b, h) + boff + n * 2048 + k * 1024); } while (0)
; #define PG8_MMA(ai, bj, At, Bt) do { __builtin_amdgcn_s_setprio(1); _Pragma("unroll") for (int m = 0; m < 4; ++m) _Pragma("unroll") for (int n = 0; n < 2; ++n) _Pragma("unroll") for (int k = 0; k < 2; ++k) \
;         acc[ai][bj][m][n] = __builtin_amdgcn_mfma_f32_16x16x32_bf16(Bt[n][k], At[m][k], acc[ai][bj][m][n], 0, 0, 0); __builtin_amdgcn_s_setprio(0); } while (0)
; #define PG8_WAIT_V(n) asm volatile("s_waitcnt vmcnt(" #n ")" ::: "memory")
; #define PG8_WAIT_L(n) asm volatile("s_waitcnt lgkmcnt(" #n ")" ::: "memory")
; #define PG8_BAR __builtin_amdgcn_s_barrier()
; #define PG8_SCHED __builtin_amdgcn_sched_barrier(0)
; template <class Epi, class Sched, bool ALIGN_EPI = false, bool SP2 = false>
; __device__ __forceinline__ void gemm_phase(PG8_LAS unsigned char* lds, const Gemm g, const Sched& S, const Epi& E) {
;     ...
;             if constexpr (SP2) {
;             PG8_LDB(B0, 0, 0); PG8_LDB(B1, 0, 1); PG8_SCHED; PG8_LDA(At, 0, 0); PG8_STAGE(PG8_SA(1, 1), a1 + hstep, voffA);
;             PG8_WAIT_V(8); PG8_WAIT_L(0); PG8_BAR; PG8_MMA(0, 0, At, B0); PG8_MMA(0, 1, At, B1); PG8_BAR; PG8_SCHED;
;             PG8_LDA(At, 0, 1); PG8_STAGE(PG8_SB(0, 0), b2, voffB); PG8_STAGE(PG8_SB(0, 1), b2 + hstep, voffB); PG8_STAGE(PG8_SA(0, 0), a2, voffA);
;             PG8_WAIT_V(8); PG8_WAIT_L(0); PG8_BAR; PG8_MMA(1, 0, At, B0); PG8_MMA(1, 1, At, B1); PG8_BAR; PG8_SCHED;
.LBB0_355:
	s_add_i32 s80, s80, 2
	s_add_u32 s82, s62, s60
	s_addc_u32 s83, s63, s61
	v_lshl_add_u64 v[232:233], v[140:141], 0, s[50:51]
	s_add_i32 m0, s98, 0xc000
	global_load_lds_dwordx4 v[232:233], off
	v_lshl_add_u64 v[232:233], v[142:143], 0, s[50:51]
	s_add_i32 m0, s98, 0xe000
	s_nop 0
	global_load_lds_dwordx4 v[232:233], off
	s_waitcnt vmcnt(8) lgkmcnt(0)
	s_barrier
	v_mfma_f32_16x16x32_bf16 v[126:129], v[148:151], v[182:185], 0
	v_mfma_f32_16x16x32_bf16 v[122:125], v[156:159], v[182:185], 0
	v_mfma_f32_16x16x32_bf16 v[118:121], v[148:151], v[208:211], 0
	v_mfma_f32_16x16x32_bf16 v[110:113], v[156:159], v[208:211], 0
	v_mfma_f32_16x16x32_bf16 v[102:105], v[148:151], v[216:219], 0
	v_mfma_f32_16x16x32_bf16 v[94:97], v[156:159], v[216:219], 0
	v_mfma_f32_16x16x32_bf16 v[86:89], v[148:151], v[224:227], 0
	v_mfma_f32_16x16x32_bf16 v[78:81], v[156:159], v[224:227], 0
	v_mfma_f32_16x16x32_bf16 v[126:129], v[152:155], v[186:189], v[126:129]
	v_mfma_f32_16x16x32_bf16 v[122:125], v[160:163], v[186:189], v[122:125]
	v_mfma_f32_16x16x32_bf16 v[118:121], v[152:155], v[212:215], v[118:121]
	v_mfma_f32_16x16x32_bf16 v[110:113], v[160:163], v[212:215], v[110:113]
	v_mfma_f32_16x16x32_bf16 v[102:105], v[152:155], v[220:223], v[102:105]
	v_mfma_f32_16x16x32_bf16 v[94:97], v[160:163], v[220:223], v[94:97]
	v_mfma_f32_16x16x32_bf16 v[86:89], v[152:155], v[228:231], v[86:89]
	v_mfma_f32_16x16x32_bf16 v[78:81], v[160:163], v[228:231], v[78:81]
	v_mfma_f32_16x16x32_bf16 v[114:117], v[164:167], v[182:185], 0
	v_mfma_f32_16x16x32_bf16 v[106:109], v[172:175], v[182:185], 0
	v_mfma_f32_16x16x32_bf16 v[98:101], v[164:167], v[208:211], 0
	v_mfma_f32_16x16x32_bf16 v[90:93], v[172:175], v[208:211], 0
	v_mfma_f32_16x16x32_bf16 v[82:85], v[164:167], v[216:219], 0
	v_mfma_f32_16x16x32_bf16 v[74:77], v[172:175], v[216:219], 0
	v_mfma_f32_16x16x32_bf16 v[70:73], v[164:167], v[224:227], 0
	v_mfma_f32_16x16x32_bf16 v[66:69], v[172:175], v[224:227], 0
	v_mfma_f32_16x16x32_bf16 v[114:117], v[168:171], v[186:189], v[114:117]
	v_mfma_f32_16x16x32_bf16 v[106:109], v[176:179], v[186:189], v[106:109]
	v_mfma_f32_16x16x32_bf16 v[98:101], v[168:171], v[212:215], v[98:101]
	v_mfma_f32_16x16x32_bf16 v[90:93], v[176:179], v[212:215], v[90:93]
	v_mfma_f32_16x16x32_bf16 v[82:85], v[168:171], v[220:223], v[82:85]
	v_mfma_f32_16x16x32_bf16 v[74:77], v[176:179], v[220:223], v[74:77]
	v_mfma_f32_16x16x32_bf16 v[70:73], v[168:171], v[228:231], v[70:73]
	v_mfma_f32_16x16x32_bf16 v[66:69], v[176:179], v[228:231], v[66:69]
	s_barrier
	s_add_i32 m0, s97, 0x10000
	ds_read_b128 v[182:185], v147 offset:16384
	ds_read_b128 v[186:189], v147 offset:17408
	ds_read_b128 v[208:211], v147 offset:18432
	ds_read_b128 v[212:215], v147 offset:19456
	ds_read_b128 v[216:219], v147 offset:20480
	ds_read_b128 v[220:223], v147 offset:21504
	ds_read_b128 v[224:227], v147 offset:22528
	ds_read_b128 v[228:231], v147 offset:23552
	global_load_lds_dwordx4 v0, s[56:57]
	s_add_i32 m0, s97, 0x12000
	s_add_u32 s38, s56, s16
	s_addc_u32 s39, s57, 0
	global_load_lds_dwordx4 v134, s[56:57]
	s_add_i32 m0, s97, 0x14000
	s_nop 0
	global_load_lds_dwordx4 v0, s[38:39]
	s_add_i32 m0, s97, 0x16000
	s_nop 0
	global_load_lds_dwordx4 v134, s[38:39]
	s_mov_b32 m0, s98
	s_nop 0
	global_load_lds_dwordx4 v130, s[62:63]
	s_mov_b32 m0, s99
	s_nop 0
	global_load_lds_dwordx4 v132, s[62:63]
	s_waitcnt vmcnt(8) lgkmcnt(0)
	s_barrier
	v_mfma_f32_16x16x32_bf16 v[62:65], v[148:151], v[182:185], 0
	v_mfma_f32_16x16x32_bf16 v[58:61], v[156:159], v[182:185], 0
	v_mfma_f32_16x16x32_bf16 v[54:57], v[148:151], v[208:211], 0
	v_mfma_f32_16x16x32_bf16 v[46:49], v[156:159], v[208:211], 0
	v_mfma_f32_16x16x32_bf16 v[38:41], v[148:151], v[216:219], 0
	v_mfma_f32_16x16x32_bf16 v[30:33], v[156:159], v[216:219], 0
	v_mfma_f32_16x16x32_bf16 v[22:25], v[148:151], v[224:227], 0
	v_mfma_f32_16x16x32_bf16 v[14:17], v[156:159], v[224:227], 0
	v_mfma_f32_16x16x32_bf16 v[62:65], v[152:155], v[186:189], v[62:65]
	v_mfma_f32_16x16x32_bf16 v[58:61], v[160:163], v[186:189], v[58:61]
	v_mfma_f32_16x16x32_bf16 v[54:57], v[152:155], v[212:215], v[54:57]
	v_mfma_f32_16x16x32_bf16 v[46:49], v[160:163], v[212:215], v[46:49]
	v_mfma_f32_16x16x32_bf16 v[38:41], v[152:155], v[220:223], v[38:41]
	v_mfma_f32_16x16x32_bf16 v[30:33], v[160:163], v[220:223], v[30:33]
	v_mfma_f32_16x16x32_bf16 v[22:25], v[152:155], v[228:231], v[22:25]
	v_mfma_f32_16x16x32_bf16 v[14:17], v[160:163], v[228:231], v[14:17]
	v_mfma_f32_16x16x32_bf16 v[50:53], v[164:167], v[182:185], 0
	v_mfma_f32_16x16x32_bf16 v[42:45], v[172:175], v[182:185], 0
	v_mfma_f32_16x16x32_bf16 v[34:37], v[164:167], v[208:211], 0
	v_mfma_f32_16x16x32_bf16 v[26:29], v[172:175], v[208:211], 0
	v_mfma_f32_16x16x32_bf16 v[18:21], v[164:167], v[216:219], 0
	v_mfma_f32_16x16x32_bf16 v[10:13], v[172:175], v[216:219], 0
	v_mfma_f32_16x16x32_bf16 v[6:9], v[164:167], v[224:227], 0
	v_mfma_f32_16x16x32_bf16 v[2:5], v[172:175], v[224:227], 0
	v_mfma_f32_16x16x32_bf16 v[50:53], v[168:171], v[186:189], v[50:53]
	v_mfma_f32_16x16x32_bf16 v[42:45], v[176:179], v[186:189], v[42:45]
	v_mfma_f32_16x16x32_bf16 v[34:37], v[168:171], v[212:215], v[34:37]
	v_mfma_f32_16x16x32_bf16 v[26:29], v[176:179], v[212:215], v[26:29]
	v_mfma_f32_16x16x32_bf16 v[18:21], v[168:171], v[220:223], v[18:21]
	v_mfma_f32_16x16x32_bf16 v[10:13], v[176:179], v[220:223], v[10:13]
	v_mfma_f32_16x16x32_bf16 v[6:9], v[168:171], v[228:231], v[6:9]
	v_mfma_f32_16x16x32_bf16 v[2:5], v[176:179], v[228:231], v[2:5]
	s_barrier
; #define PG8_STAGE(bufoff, gbase, voff) do { _Pragma("unroll") for (int _i = 0; _i < 2; ++_i) \
;         __builtin_amdgcn_global_load_lds((const unsigned*)((const char*)(gbase) + (voff)[_i]), (PG8_LAS unsigned*)(lds + (bufoff) + ldsw + _i * 8192), 16, 0, 0); } while (0)
; #define PG8_LDA(dst, b, h) do { _Pragma("unroll") for (int m = 0; m < 4; ++m) _Pragma("unroll") for (int k = 0; k < 2; ++k) dst[m][k] = *(const PG8_LAS bf16x8*)(lds + PG8_SA(b, h) + aoff + m * 2048 + k * 1024); } while (0)
; #define PG8_LDB(dst, b, h) do { _Pragma("unroll") for (int n = 0; n < 2; ++n) _Pragma("unroll") for (int k = 0; k < 2; ++k) dst[n][k] = *(const PG8_LAS bf16x8*)(lds + PG8_SB(b, h) + boff + n * 2048 + k * 1024); } while (0)
; #define PG8_MMA(ai, bj, At, Bt) do { __builtin_amdgcn_s_setprio(1); _Pragma("unroll") for (int m = 0; m < 4; ++m) _Pragma("unroll") for (int n = 0; n < 2; ++n) _Pragma("unroll") for (int k = 0; k < 2; ++k) \
;         acc[ai][bj][m][n] = __builtin_amdgcn_mfma_f32_16x16x32_bf16(Bt[n][k], At[m][k], acc[ai][bj][m][n], 0, 0, 0); __builtin_amdgcn_s_setprio(0); } while (0)
; #define PG8_WAIT_V(n) asm volatile("s_waitcnt vmcnt(" #n ")" ::: "memory")
; #define PG8_WAIT_L(n) asm volatile("s_waitcnt lgkmcnt(" #n ")" ::: "memory")
; #define PG8_BAR __builtin_amdgcn_s_barrier()
; template <class Epi, class Sched, bool ALIGN_EPI = false, bool SP2 = false>
; __device__ __forceinline__ void gemm_phase(PG8_LAS unsigned char* lds, const Gemm g, const Sched& S, const Epi& E) {
;     ...
;         for (int t = 0; t < nt; t += 2) {
;             const bool last = (t == nt - 2);
;             const char* a1 = cA + (long)(t + 1) * ks;
;             const char* a2 = last ? nA : cA + (long)(t + 2) * ks; const char* b2 = last ? nB : cB + (long)(t + 2) * ks;
;             const long ks3 = last ? nks : ks; const char* a3 = a2 + ks3; const char* b3 = b2 + ks3;
;     ...
;             PG8_LDB(B0, 1, 0); PG8_LDB(B1, 1, 1); PG8_SCHED; PG8_LDA(At, 1, 0); PG8_STAGE(PG8_SA(0, 1), a2 + hstep, voffA);
;             PG8_WAIT_V(8); PG8_WAIT_L(0); PG8_BAR; PG8_MMA(0, 0, At, B0); PG8_MMA(0, 1, At, B1); PG8_BAR; PG8_SCHED;
;             PG8_LDA(At, 1, 1); PG8_STAGE(PG8_SB(1, 0), b3, voffB); PG8_STAGE(PG8_SB(1, 1), b3 + hstep, voffB); PG8_STAGE(PG8_SA(1, 0), a3, voffA);
;             PG8_WAIT_V(8); PG8_WAIT_L(0); PG8_BAR; PG8_MMA(1, 0, At, B0); PG8_MMA(1, 1, At, B1); PG8_BAR; PG8_SCHED;
	ds_read_b128 v[148:151], v242 offset:32768
	ds_read_b128 v[152:155], v242 offset:33792
	ds_read_b128 v[156:159], v242 offset:34816
	ds_read_b128 v[160:163], v242 offset:35840
	ds_read_b128 v[164:167], v242 offset:49152
	ds_read_b128 v[168:171], v242 offset:50176
	ds_read_b128 v[172:175], v242 offset:51200
	ds_read_b128 v[176:179], v242 offset:52224
	s_add_u32 s38, s62, s16
	s_addc_u32 s39, s63, 0
	s_mov_b32 m0, s68
	ds_read_b128 v[182:185], v147 offset:32768
	ds_read_b128 v[186:189], v147 offset:33792
	ds_read_b128 v[208:211], v147 offset:34816
	ds_read_b128 v[212:215], v147 offset:35840
	ds_read_b128 v[216:219], v147 offset:36864
	ds_read_b128 v[220:223], v147 offset:37888
	ds_read_b128 v[224:227], v147 offset:38912
	ds_read_b128 v[228:231], v147 offset:39936
	global_load_lds_dwordx4 v130, s[38:39]
	s_mov_b32 m0, s64
	s_nop 0
	global_load_lds_dwordx4 v132, s[38:39]
	s_waitcnt vmcnt(8) lgkmcnt(0)
	s_barrier
	v_mfma_f32_16x16x32_bf16 v[126:129], v[148:151], v[182:185], v[126:129]
	v_mfma_f32_16x16x32_bf16 v[122:125], v[156:159], v[182:185], v[122:125]
	v_mfma_f32_16x16x32_bf16 v[118:121], v[148:151], v[208:211], v[118:121]
	v_mfma_f32_16x16x32_bf16 v[110:113], v[156:159], v[208:211], v[110:113]
	v_mfma_f32_16x16x32_bf16 v[102:105], v[148:151], v[216:219], v[102:105]
	v_mfma_f32_16x16x32_bf16 v[94:97], v[156:159], v[216:219], v[94:97]
	v_mfma_f32_16x16x32_bf16 v[86:89], v[148:151], v[224:227], v[86:89]
	v_mfma_f32_16x16x32_bf16 v[78:81], v[156:159], v[224:227], v[78:81]
	v_mfma_f32_16x16x32_bf16 v[126:129], v[152:155], v[186:189], v[126:129]
	v_mfma_f32_16x16x32_bf16 v[122:125], v[160:163], v[186:189], v[122:125]
	v_mfma_f32_16x16x32_bf16 v[118:121], v[152:155], v[212:215], v[118:121]
	v_mfma_f32_16x16x32_bf16 v[110:113], v[160:163], v[212:215], v[110:113]
	v_mfma_f32_16x16x32_bf16 v[102:105], v[152:155], v[220:223], v[102:105]
	v_mfma_f32_16x16x32_bf16 v[94:97], v[160:163], v[220:223], v[94:97]
	v_mfma_f32_16x16x32_bf16 v[86:89], v[152:155], v[228:231], v[86:89]
	v_mfma_f32_16x16x32_bf16 v[78:81], v[160:163], v[228:231], v[78:81]
	v_mfma_f32_16x16x32_bf16 v[114:117], v[164:167], v[182:185], v[114:117]
	v_mfma_f32_16x16x32_bf16 v[106:109], v[172:175], v[182:185], v[106:109]
	v_mfma_f32_16x16x32_bf16 v[98:101], v[164:167], v[208:211], v[98:101]
	v_mfma_f32_16x16x32_bf16 v[90:93], v[172:175], v[208:211], v[90:93]
	v_mfma_f32_16x16x32_bf16 v[82:85], v[164:167], v[216:219], v[82:85]
	v_mfma_f32_16x16x32_bf16 v[74:77], v[172:175], v[216:219], v[74:77]
	v_mfma_f32_16x16x32_bf16 v[70:73], v[164:167], v[224:227], v[70:73]
	v_mfma_f32_16x16x32_bf16 v[66:69], v[172:175], v[224:227], v[66:69]
	v_mfma_f32_16x16x32_bf16 v[114:117], v[168:171], v[186:189], v[114:117]
	v_mfma_f32_16x16x32_bf16 v[106:109], v[176:179], v[186:189], v[106:109]
	v_mfma_f32_16x16x32_bf16 v[98:101], v[168:171], v[212:215], v[98:101]
	v_mfma_f32_16x16x32_bf16 v[90:93], v[176:179], v[212:215], v[90:93]
	v_mfma_f32_16x16x32_bf16 v[82:85], v[168:171], v[220:223], v[82:85]
	v_mfma_f32_16x16x32_bf16 v[74:77], v[176:179], v[220:223], v[74:77]
	v_mfma_f32_16x16x32_bf16 v[70:73], v[168:171], v[228:231], v[70:73]
	v_mfma_f32_16x16x32_bf16 v[66:69], v[176:179], v[228:231], v[66:69]
	s_barrier
	s_add_u32 s38, s56, s60
	s_addc_u32 s39, s57, s61
	s_add_i32 m0, s97, 0x18000
	ds_read_b128 v[182:185], v147 offset:49152
	ds_read_b128 v[186:189], v147 offset:50176
	ds_read_b128 v[208:211], v147 offset:51200
	ds_read_b128 v[212:215], v147 offset:52224
	ds_read_b128 v[216:219], v147 offset:53248
	ds_read_b128 v[220:223], v147 offset:54272
	ds_read_b128 v[224:227], v147 offset:55296
	ds_read_b128 v[228:231], v147 offset:56320
	global_load_lds_dwordx4 v0, s[38:39]
	s_add_i32 m0, s97, 0x1a000
	s_nop 0
	global_load_lds_dwordx4 v134, s[38:39]
	s_add_u32 s38, s38, s16
	s_addc_u32 s39, s39, 0
	s_add_i32 m0, s97, 0x1c000
	global_load_lds_dwordx4 v0, s[38:39]
	s_add_i32 m0, s97, 0x1e000
	s_nop 0
	global_load_lds_dwordx4 v134, s[38:39]
	s_mov_b32 m0, s72
	s_nop 0
	global_load_lds_dwordx4 v130, s[82:83]
	s_mov_b32 m0, s73
	s_nop 0
	global_load_lds_dwordx4 v132, s[82:83]
	s_add_u32 s50, s50, s48
	s_addc_u32 s51, s51, s49
	s_cmp_ge_u32 s80, s13
	s_cselect_b64 vcc, -1, 0
	s_cbranch_scc1 .Lgemm_ctl_done_p
	s_cmp_eq_u32 s88, s80
	s_cbranch_scc1 .Lgemm_ctl_last_p
	s_add_u32 s62, s18, s50
	s_addc_u32 s63, s19, s51
	s_add_u32 s56, s87, s50
	s_addc_u32 s57, s33, s51
	s_mov_b64 s[60:61], s[44:45]
	s_branch .Lgemm_ctl_join_p

; #define PG8_STAGE(bufoff, gbase, voff) do { _Pragma("unroll") for (int _i = 0; _i < 2; ++_i) \
;         __builtin_amdgcn_global_load_lds((const unsigned*)((const char*)(gbase) + (voff)[_i]), (PG8_LAS unsigned*)(lds + (bufoff) + ldsw + _i * 8192), 16, 0, 0); } while (0)
; #define PG8_LDA(dst, b, h) do { _Pragma("unroll") for (int m = 0; m < 4; ++m) _Pragma("unroll") for (int k = 0; k < 2; ++k) dst[m][k] = *(const PG8_LAS bf16x8*)(lds + PG8_SA(b, h) + aoff + m * 2048 + k * 1024); } while (0)
; #define PG8_LDB(dst, b, h) do { _Pragma("unroll") for (int n = 0; n < 2; ++n) _Pragma("unroll") for (int k = 0; k < 2; ++k) dst[n][k] = *(const PG8_LAS bf16x8*)(lds + PG8_SB(b, h) + boff + n * 2048 + k * 1024); } while (0)
; #define PG8_MMA(ai, bj, At, Bt) do { __builtin_amdgcn_s_setprio(1); _Pragma("unroll") for (int m = 0; m < 4; ++m) _Pragma("unroll") for (int n = 0; n < 2; ++n) _Pragma("unroll") for (int k = 0; k < 2; ++k) \
;         acc[ai][bj][m][n] = __builtin_amdgcn_mfma_f32_16x16x32_bf16(Bt[n][k], At[m][k], acc[ai][bj][m][n], 0, 0, 0); __builtin_amdgcn_s_setprio(0); } while (0)
; #define PG8_WAIT_V(n) asm volatile("s_waitcnt vmcnt(" #n ")" ::: "memory")
; #define PG8_WAIT_L(n) asm volatile("s_waitcnt lgkmcnt(" #n ")" ::: "memory")
; #define PG8_BAR __builtin_amdgcn_s_barrier()
; template <class Epi, class Sched, bool ALIGN_EPI = false, bool SP2 = false>
; __device__ __forceinline__ void gemm_phase(PG8_LAS unsigned char* lds, const Gemm g, const Sched& S, const Epi& E) {
;     ...
;             PG8_WAIT_V(8); PG8_WAIT_L(0); PG8_BAR; PG8_MMA(0, 0, At, B0); PG8_MMA(0, 1, At, B1); PG8_BAR; PG8_SCHED;
;             PG8_LDA(At, 0, 1); PG8_STAGE(PG8_SB(0, 0), b2, voffB); PG8_STAGE(PG8_SB(0, 1), b2 + hstep, voffB); PG8_STAGE(PG8_SA(0, 0), a2, voffA);
;             PG8_WAIT_V(8); PG8_WAIT_L(0); PG8_BAR; PG8_MMA(1, 0, At, B0); PG8_MMA(1, 1, At, B1); PG8_BAR; PG8_SCHED;
;             PG8_LDB(B0, 1, 0); PG8_LDB(B1, 1, 1); PG8_SCHED; PG8_LDA(At, 1, 0); PG8_STAGE(PG8_SA(0, 1), a2 + hstep, voffA);
;             PG8_WAIT_V(8); PG8_WAIT_L(0); PG8_BAR; PG8_MMA(0, 0, At, B0); PG8_MMA(0, 1, At, B1); PG8_BAR; PG8_SCHED;
;             PG8_LDA(At, 1, 1); PG8_STAGE(PG8_SB(1, 0), b3, voffB); PG8_STAGE(PG8_SB(1, 1), b3 + hstep, voffB); PG8_STAGE(PG8_SA(1, 0), a3, voffA);
;             PG8_WAIT_V(8); PG8_WAIT_L(0); PG8_BAR; PG8_MMA(1, 0, At, B0); PG8_MMA(1, 1, At, B1); PG8_BAR; PG8_SCHED;
.Lgemm_ctl_done_p:
	s_waitcnt vmcnt(8) lgkmcnt(0)
	s_barrier
	v_mfma_f32_16x16x32_bf16 v[62:65], v[148:151], v[182:185], v[62:65]
	v_mfma_f32_16x16x32_bf16 v[58:61], v[156:159], v[182:185], v[58:61]
	v_mfma_f32_16x16x32_bf16 v[54:57], v[148:151], v[208:211], v[54:57]
	v_mfma_f32_16x16x32_bf16 v[46:49], v[156:159], v[208:211], v[46:49]
	v_mfma_f32_16x16x32_bf16 v[38:41], v[148:151], v[216:219], v[38:41]
	v_mfma_f32_16x16x32_bf16 v[30:33], v[156:159], v[216:219], v[30:33]
	v_mfma_f32_16x16x32_bf16 v[22:25], v[148:151], v[224:227], v[22:25]
	v_mfma_f32_16x16x32_bf16 v[14:17], v[156:159], v[224:227], v[14:17]
	v_mfma_f32_16x16x32_bf16 v[62:65], v[152:155], v[186:189], v[62:65]
	v_mfma_f32_16x16x32_bf16 v[58:61], v[160:163], v[186:189], v[58:61]
	v_mfma_f32_16x16x32_bf16 v[54:57], v[152:155], v[212:215], v[54:57]
	v_mfma_f32_16x16x32_bf16 v[46:49], v[160:163], v[212:215], v[46:49]
	v_mfma_f32_16x16x32_bf16 v[38:41], v[152:155], v[220:223], v[38:41]
	v_mfma_f32_16x16x32_bf16 v[30:33], v[160:163], v[220:223], v[30:33]
	v_mfma_f32_16x16x32_bf16 v[22:25], v[152:155], v[228:231], v[22:25]
	v_mfma_f32_16x16x32_bf16 v[14:17], v[160:163], v[228:231], v[14:17]
	v_mfma_f32_16x16x32_bf16 v[50:53], v[164:167], v[182:185], v[50:53]
	v_mfma_f32_16x16x32_bf16 v[42:45], v[172:175], v[182:185], v[42:45]
	v_mfma_f32_16x16x32_bf16 v[34:37], v[164:167], v[208:211], v[34:37]
	v_mfma_f32_16x16x32_bf16 v[26:29], v[172:175], v[208:211], v[26:29]
	v_mfma_f32_16x16x32_bf16 v[18:21], v[164:167], v[216:219], v[18:21]
	v_mfma_f32_16x16x32_bf16 v[10:13], v[172:175], v[216:219], v[10:13]
	v_mfma_f32_16x16x32_bf16 v[6:9], v[164:167], v[224:227], v[6:9]
	v_mfma_f32_16x16x32_bf16 v[2:5], v[172:175], v[224:227], v[2:5]
	v_mfma_f32_16x16x32_bf16 v[50:53], v[168:171], v[186:189], v[50:53]
	v_mfma_f32_16x16x32_bf16 v[42:45], v[176:179], v[186:189], v[42:45]
	v_mfma_f32_16x16x32_bf16 v[34:37], v[168:171], v[212:215], v[34:37]
	v_mfma_f32_16x16x32_bf16 v[26:29], v[176:179], v[212:215], v[26:29]
	v_mfma_f32_16x16x32_bf16 v[18:21], v[168:171], v[220:223], v[18:21]
	v_mfma_f32_16x16x32_bf16 v[10:13], v[176:179], v[220:223], v[10:13]
	v_mfma_f32_16x16x32_bf16 v[6:9], v[168:171], v[228:231], v[6:9]
	v_mfma_f32_16x16x32_bf16 v[2:5], v[176:179], v[228:231], v[2:5]
	s_barrier
	s_cbranch_vccz .Lgemm_head
	s_branch .LBB0_360
.Lgemm_head:
	ds_read_b128 v[148:151], v242
	ds_read_b128 v[152:155], v242 offset:1024
	ds_read_b128 v[156:159], v242 offset:2048
	ds_read_b128 v[160:163], v242 offset:3072
	ds_read_b128 v[164:167], v242 offset:16384
	ds_read_b128 v[168:171], v242 offset:17408
	ds_read_b128 v[172:175], v242 offset:18432
	ds_read_b128 v[176:179], v242 offset:19456
	v_lshl_add_u64 v[232:233], v[140:141], 0, s[50:51]
	s_add_i32 m0, s98, 0xc000
	ds_read_b128 v[182:185], v147
	ds_read_b128 v[186:189], v147 offset:1024
	ds_read_b128 v[208:211], v147 offset:2048
	ds_read_b128 v[212:215], v147 offset:3072
	ds_read_b128 v[216:219], v147 offset:4096
	ds_read_b128 v[220:223], v147 offset:5120
	ds_read_b128 v[224:227], v147 offset:6144
	ds_read_b128 v[228:231], v147 offset:7168
	global_load_lds_dwordx4 v[232:233], off
	v_lshl_add_u64 v[232:233], v[142:143], 0, s[50:51]
	s_add_i32 m0, s98, 0xe000
	s_nop 0
	global_load_lds_dwordx4 v[232:233], off
	s_waitcnt vmcnt(8) lgkmcnt(0)
	s_barrier
	v_mfma_f32_16x16x32_bf16 v[126:129], v[148:151], v[182:185], v[126:129]
	v_mfma_f32_16x16x32_bf16 v[122:125], v[156:159], v[182:185], v[122:125]
	v_mfma_f32_16x16x32_bf16 v[118:121], v[148:151], v[208:211], v[118:121]
	v_mfma_f32_16x16x32_bf16 v[110:113], v[156:159], v[208:211], v[110:113]
	v_mfma_f32_16x16x32_bf16 v[102:105], v[148:151], v[216:219], v[102:105]
	v_mfma_f32_16x16x32_bf16 v[94:97], v[156:159], v[216:219], v[94:97]
	v_mfma_f32_16x16x32_bf16 v[86:89], v[148:151], v[224:227], v[86:89]
	v_mfma_f32_16x16x32_bf16 v[78:81], v[156:159], v[224:227], v[78:81]
	v_mfma_f32_16x16x32_bf16 v[126:129], v[152:155], v[186:189], v[126:129]
	v_mfma_f32_16x16x32_bf16 v[122:125], v[160:163], v[186:189], v[122:125]
	v_mfma_f32_16x16x32_bf16 v[118:121], v[152:155], v[212:215], v[118:121]
	v_mfma_f32_16x16x32_bf16 v[110:113], v[160:163], v[212:215], v[110:113]
	v_mfma_f32_16x16x32_bf16 v[102:105], v[152:155], v[220:223], v[102:105]
	v_mfma_f32_16x16x32_bf16 v[94:97], v[160:163], v[220:223], v[94:97]
	v_mfma_f32_16x16x32_bf16 v[86:89], v[152:155], v[228:231], v[86:89]
	v_mfma_f32_16x16x32_bf16 v[78:81], v[160:163], v[228:231], v[78:81]
	v_mfma_f32_16x16x32_bf16 v[114:117], v[164:167], v[182:185], v[114:117]
	v_mfma_f32_16x16x32_bf16 v[106:109], v[172:175], v[182:185], v[106:109]
	v_mfma_f32_16x16x32_bf16 v[98:101], v[164:167], v[208:211], v[98:101]
	v_mfma_f32_16x16x32_bf16 v[90:93], v[172:175], v[208:211], v[90:93]
	v_mfma_f32_16x16x32_bf16 v[82:85], v[164:167], v[216:219], v[82:85]
	v_mfma_f32_16x16x32_bf16 v[74:77], v[172:175], v[216:219], v[74:77]
	v_mfma_f32_16x16x32_bf16 v[70:73], v[164:167], v[224:227], v[70:73]
	v_mfma_f32_16x16x32_bf16 v[66:69], v[172:175], v[224:227], v[66:69]
	v_mfma_f32_16x16x32_bf16 v[114:117], v[168:171], v[186:189], v[114:117]
	v_mfma_f32_16x16x32_bf16 v[106:109], v[176:179], v[186:189], v[106:109]
	v_mfma_f32_16x16x32_bf16 v[98:101], v[168:171], v[212:215], v[98:101]
	v_mfma_f32_16x16x32_bf16 v[90:93], v[176:179], v[212:215], v[90:93]
	v_mfma_f32_16x16x32_bf16 v[82:85], v[168:171], v[220:223], v[82:85]
	v_mfma_f32_16x16x32_bf16 v[74:77], v[176:179], v[220:223], v[74:77]
	v_mfma_f32_16x16x32_bf16 v[70:73], v[168:171], v[228:231], v[70:73]
	v_mfma_f32_16x16x32_bf16 v[66:69], v[176:179], v[228:231], v[66:69]
	s_barrier
; #define PG8_STAGE(bufoff, gbase, voff) do { _Pragma("unroll") for (int _i = 0; _i < 2; ++_i) \
;         __builtin_amdgcn_global_load_lds((const unsigned*)((const char*)(gbase) + (voff)[_i]), (PG8_LAS unsigned*)(lds + (bufoff) + ldsw + _i * 8192), 16, 0, 0); } while (0)
; #define PG8_LDA(dst, b, h) do { _Pragma("unroll") for (int m = 0; m < 4; ++m) _Pragma("unroll") for (int k = 0; k < 2; ++k) dst[m][k] = *(const PG8_LAS bf16x8*)(lds + PG8_SA(b, h) + aoff + m * 2048 + k * 1024); } while (0)
; #define PG8_LDB(dst, b, h) do { _Pragma("unroll") for (int n = 0; n < 2; ++n) _Pragma("unroll") for (int k = 0; k < 2; ++k) dst[n][k] = *(const PG8_LAS bf16x8*)(lds + PG8_SB(b, h) + boff + n * 2048 + k * 1024); } while (0)
; #define PG8_MMA(ai, bj, At, Bt) do { __builtin_amdgcn_s_setprio(1); _Pragma("unroll") for (int m = 0; m < 4; ++m) _Pragma("unroll") for (int n = 0; n < 2; ++n) _Pragma("unroll") for (int k = 0; k < 2; ++k) \
;         acc[ai][bj][m][n] = __builtin_amdgcn_mfma_f32_16x16x32_bf16(Bt[n][k], At[m][k], acc[ai][bj][m][n], 0, 0, 0); __builtin_amdgcn_s_setprio(0); } while (0)
; #define PG8_WAIT_V(n) asm volatile("s_waitcnt vmcnt(" #n ")" ::: "memory")
; #define PG8_WAIT_L(n) asm volatile("s_waitcnt lgkmcnt(" #n ")" ::: "memory")
; #define PG8_BAR __builtin_amdgcn_s_barrier()
; #define PG8_SCHED __builtin_amdgcn_sched_barrier(0)
; template <class Epi, class Sched, bool ALIGN_EPI = false, bool SP2 = false>
; __device__ __forceinline__ void gemm_phase(PG8_LAS unsigned char* lds, const Gemm g, const Sched& S, const Epi& E) {
;     ...
;             PG8_LDA(At, 0, 1); PG8_STAGE(PG8_SB(0, 0), b2, voffB); PG8_STAGE(PG8_SB(0, 1), b2 + hstep, voffB); PG8_STAGE(PG8_SA(0, 0), a2, voffA);
;             PG8_WAIT_V(8); PG8_WAIT_L(0); PG8_BAR; PG8_MMA(1, 0, At, B0); PG8_MMA(1, 1, At, B1); PG8_BAR; PG8_SCHED;
;             PG8_LDB(B0, 1, 0); PG8_LDB(B1, 1, 1); PG8_SCHED; PG8_LDA(At, 1, 0); PG8_STAGE(PG8_SA(0, 1), a2 + hstep, voffA);
;             PG8_WAIT_V(8); PG8_WAIT_L(0); PG8_BAR; PG8_MMA(0, 0, At, B0); PG8_MMA(0, 1, At, B1); PG8_BAR; PG8_SCHED;
	s_add_i32 m0, s97, 0x10000
	ds_read_b128 v[182:185], v147 offset:16384
	ds_read_b128 v[186:189], v147 offset:17408
	ds_read_b128 v[208:211], v147 offset:18432
	ds_read_b128 v[212:215], v147 offset:19456
	ds_read_b128 v[216:219], v147 offset:20480
	ds_read_b128 v[220:223], v147 offset:21504
	ds_read_b128 v[224:227], v147 offset:22528
	ds_read_b128 v[228:231], v147 offset:23552
	global_load_lds_dwordx4 v0, s[56:57]
	s_add_i32 m0, s97, 0x12000
	s_add_u32 s38, s56, s16
	s_addc_u32 s39, s57, 0
	global_load_lds_dwordx4 v134, s[56:57]
	s_add_i32 m0, s97, 0x14000
	s_nop 0
	global_load_lds_dwordx4 v0, s[38:39]
	s_add_i32 m0, s97, 0x16000
	s_nop 0
	global_load_lds_dwordx4 v134, s[38:39]
	s_mov_b32 m0, s98
	s_nop 0
	global_load_lds_dwordx4 v130, s[62:63]
	s_mov_b32 m0, s99
	s_nop 0
	global_load_lds_dwordx4 v132, s[62:63]
	s_waitcnt vmcnt(8) lgkmcnt(0)
	s_barrier
	v_mfma_f32_16x16x32_bf16 v[62:65], v[148:151], v[182:185], v[62:65]
	v_mfma_f32_16x16x32_bf16 v[58:61], v[156:159], v[182:185], v[58:61]
	v_mfma_f32_16x16x32_bf16 v[54:57], v[148:151], v[208:211], v[54:57]
	v_mfma_f32_16x16x32_bf16 v[46:49], v[156:159], v[208:211], v[46:49]
	v_mfma_f32_16x16x32_bf16 v[38:41], v[148:151], v[216:219], v[38:41]
	v_mfma_f32_16x16x32_bf16 v[30:33], v[156:159], v[216:219], v[30:33]
	v_mfma_f32_16x16x32_bf16 v[22:25], v[148:151], v[224:227], v[22:25]
	v_mfma_f32_16x16x32_bf16 v[14:17], v[156:159], v[224:227], v[14:17]
	v_mfma_f32_16x16x32_bf16 v[62:65], v[152:155], v[186:189], v[62:65]
	v_mfma_f32_16x16x32_bf16 v[58:61], v[160:163], v[186:189], v[58:61]
	v_mfma_f32_16x16x32_bf16 v[54:57], v[152:155], v[212:215], v[54:57]
	v_mfma_f32_16x16x32_bf16 v[46:49], v[160:163], v[212:215], v[46:49]
	v_mfma_f32_16x16x32_bf16 v[38:41], v[152:155], v[220:223], v[38:41]
	v_mfma_f32_16x16x32_bf16 v[30:33], v[160:163], v[220:223], v[30:33]
	v_mfma_f32_16x16x32_bf16 v[22:25], v[152:155], v[228:231], v[22:25]
	v_mfma_f32_16x16x32_bf16 v[14:17], v[160:163], v[228:231], v[14:17]
	v_mfma_f32_16x16x32_bf16 v[50:53], v[164:167], v[182:185], v[50:53]
	v_mfma_f32_16x16x32_bf16 v[42:45], v[172:175], v[182:185], v[42:45]
	v_mfma_f32_16x16x32_bf16 v[34:37], v[164:167], v[208:211], v[34:37]
	v_mfma_f32_16x16x32_bf16 v[26:29], v[172:175], v[208:211], v[26:29]
	v_mfma_f32_16x16x32_bf16 v[18:21], v[164:167], v[216:219], v[18:21]
	v_mfma_f32_16x16x32_bf16 v[10:13], v[172:175], v[216:219], v[10:13]
	v_mfma_f32_16x16x32_bf16 v[6:9], v[164:167], v[224:227], v[6:9]
	v_mfma_f32_16x16x32_bf16 v[2:5], v[172:175], v[224:227], v[2:5]
	v_mfma_f32_16x16x32_bf16 v[50:53], v[168:171], v[186:189], v[50:53]
	v_mfma_f32_16x16x32_bf16 v[42:45], v[176:179], v[186:189], v[42:45]
	v_mfma_f32_16x16x32_bf16 v[34:37], v[168:171], v[212:215], v[34:37]
	v_mfma_f32_16x16x32_bf16 v[26:29], v[176:179], v[212:215], v[26:29]
	v_mfma_f32_16x16x32_bf16 v[18:21], v[168:171], v[220:223], v[18:21]
	v_mfma_f32_16x16x32_bf16 v[10:13], v[176:179], v[220:223], v[10:13]
	v_mfma_f32_16x16x32_bf16 v[6:9], v[168:171], v[228:231], v[6:9]
	v_mfma_f32_16x16x32_bf16 v[2:5], v[176:179], v[228:231], v[2:5]
	s_barrier
	ds_read_b128 v[148:151], v242 offset:32768
	ds_read_b128 v[152:155], v242 offset:33792
	ds_read_b128 v[156:159], v242 offset:34816
	ds_read_b128 v[160:163], v242 offset:35840
	ds_read_b128 v[164:167], v242 offset:49152
	ds_read_b128 v[168:171], v242 offset:50176
	ds_read_b128 v[172:175], v242 offset:51200
	ds_read_b128 v[176:179], v242 offset:52224
	s_add_u32 s38, s62, s16
	s_addc_u32 s39, s63, 0
	s_mov_b32 m0, s68
	ds_read_b128 v[182:185], v147 offset:32768
	ds_read_b128 v[186:189], v147 offset:33792
	ds_read_b128 v[208:211], v147 offset:34816
	ds_read_b128 v[212:215], v147 offset:35840
	ds_read_b128 v[216:219], v147 offset:36864
	ds_read_b128 v[220:223], v147 offset:37888
	ds_read_b128 v[224:227], v147 offset:38912
	ds_read_b128 v[228:231], v147 offset:39936
	global_load_lds_dwordx4 v130, s[38:39]
	s_mov_b32 m0, s64
	s_nop 0
	global_load_lds_dwordx4 v132, s[38:39]
	s_waitcnt vmcnt(8) lgkmcnt(0)
	s_barrier
; #define PG8_STAGE(bufoff, gbase, voff) do { _Pragma("unroll") for (int _i = 0; _i < 2; ++_i) \
;         __builtin_amdgcn_global_load_lds((const unsigned*)((const char*)(gbase) + (voff)[_i]), (PG8_LAS unsigned*)(lds + (bufoff) + ldsw + _i * 8192), 16, 0, 0); } while (0)
; #define PG8_LDA(dst, b, h) do { _Pragma("unroll") for (int m = 0; m < 4; ++m) _Pragma("unroll") for (int k = 0; k < 2; ++k) dst[m][k] = *(const PG8_LAS bf16x8*)(lds + PG8_SA(b, h) + aoff + m * 2048 + k * 1024); } while (0)
; #define PG8_MMA(ai, bj, At, Bt) do { __builtin_amdgcn_s_setprio(1); _Pragma("unroll") for (int m = 0; m < 4; ++m) _Pragma("unroll") for (int n = 0; n < 2; ++n) _Pragma("unroll") for (int k = 0; k < 2; ++k) \
;         acc[ai][bj][m][n] = __builtin_amdgcn_mfma_f32_16x16x32_bf16(Bt[n][k], At[m][k], acc[ai][bj][m][n], 0, 0, 0); __builtin_amdgcn_s_setprio(0); } while (0)
; #define PG8_WAIT_V(n) asm volatile("s_waitcnt vmcnt(" #n ")" ::: "memory")
; #define PG8_WAIT_L(n) asm volatile("s_waitcnt lgkmcnt(" #n ")" ::: "memory")
; #define PG8_BAR __builtin_amdgcn_s_barrier()
; #define PG8_SCHED __builtin_amdgcn_sched_barrier(0)
; template <class Epi, class Sched, bool ALIGN_EPI = false, bool SP2 = false>
; __device__ __forceinline__ void gemm_phase(PG8_LAS unsigned char* lds, const Gemm g, const Sched& S, const Epi& E) {
;     ...
;         for (int t = 0; t < nt; t += 2) {
;             const bool last = (t == nt - 2);
;             const char* a1 = cA + (long)(t + 1) * ks;
;             const char* a2 = last ? nA : cA + (long)(t + 2) * ks; const char* b2 = last ? nB : cB + (long)(t + 2) * ks;
;             const long ks3 = last ? nks : ks; const char* a3 = a2 + ks3; const char* b3 = b2 + ks3;
;     ...
;             PG8_WAIT_V(8); PG8_WAIT_L(0); PG8_BAR; PG8_MMA(0, 0, At, B0); PG8_MMA(0, 1, At, B1); PG8_BAR; PG8_SCHED;
;             PG8_LDA(At, 1, 1); PG8_STAGE(PG8_SB(1, 0), b3, voffB); PG8_STAGE(PG8_SB(1, 1), b3 + hstep, voffB); PG8_STAGE(PG8_SA(1, 0), a3, voffA);
;             PG8_WAIT_V(8); PG8_WAIT_L(0); PG8_BAR; PG8_MMA(1, 0, At, B0); PG8_MMA(1, 1, At, B1); PG8_BAR; PG8_SCHED;
	v_mfma_f32_16x16x32_bf16 v[126:129], v[148:151], v[182:185], v[126:129]
	v_mfma_f32_16x16x32_bf16 v[122:125], v[156:159], v[182:185], v[122:125]
	v_mfma_f32_16x16x32_bf16 v[118:121], v[148:151], v[208:211], v[118:121]
	v_mfma_f32_16x16x32_bf16 v[110:113], v[156:159], v[208:211], v[110:113]
	v_mfma_f32_16x16x32_bf16 v[102:105], v[148:151], v[216:219], v[102:105]
	v_mfma_f32_16x16x32_bf16 v[94:97], v[156:159], v[216:219], v[94:97]
	v_mfma_f32_16x16x32_bf16 v[86:89], v[148:151], v[224:227], v[86:89]
	v_mfma_f32_16x16x32_bf16 v[78:81], v[156:159], v[224:227], v[78:81]
	v_mfma_f32_16x16x32_bf16 v[126:129], v[152:155], v[186:189], v[126:129]
	v_mfma_f32_16x16x32_bf16 v[122:125], v[160:163], v[186:189], v[122:125]
	v_mfma_f32_16x16x32_bf16 v[118:121], v[152:155], v[212:215], v[118:121]
	v_mfma_f32_16x16x32_bf16 v[110:113], v[160:163], v[212:215], v[110:113]
	v_mfma_f32_16x16x32_bf16 v[102:105], v[152:155], v[220:223], v[102:105]
	v_mfma_f32_16x16x32_bf16 v[94:97], v[160:163], v[220:223], v[94:97]
	v_mfma_f32_16x16x32_bf16 v[86:89], v[152:155], v[228:231], v[86:89]
	v_mfma_f32_16x16x32_bf16 v[78:81], v[160:163], v[228:231], v[78:81]
	v_mfma_f32_16x16x32_bf16 v[114:117], v[164:167], v[182:185], v[114:117]
	v_mfma_f32_16x16x32_bf16 v[106:109], v[172:175], v[182:185], v[106:109]
	v_mfma_f32_16x16x32_bf16 v[98:101], v[164:167], v[208:211], v[98:101]
	v_mfma_f32_16x16x32_bf16 v[90:93], v[172:175], v[208:211], v[90:93]
	v_mfma_f32_16x16x32_bf16 v[82:85], v[164:167], v[216:219], v[82:85]
	v_mfma_f32_16x16x32_bf16 v[74:77], v[172:175], v[216:219], v[74:77]
	v_mfma_f32_16x16x32_bf16 v[70:73], v[164:167], v[224:227], v[70:73]
	v_mfma_f32_16x16x32_bf16 v[66:69], v[172:175], v[224:227], v[66:69]
	v_mfma_f32_16x16x32_bf16 v[114:117], v[168:171], v[186:189], v[114:117]
	v_mfma_f32_16x16x32_bf16 v[106:109], v[176:179], v[186:189], v[106:109]
	v_mfma_f32_16x16x32_bf16 v[98:101], v[168:171], v[212:215], v[98:101]
	v_mfma_f32_16x16x32_bf16 v[90:93], v[176:179], v[212:215], v[90:93]
	v_mfma_f32_16x16x32_bf16 v[82:85], v[168:171], v[220:223], v[82:85]
	v_mfma_f32_16x16x32_bf16 v[74:77], v[176:179], v[220:223], v[74:77]
	v_mfma_f32_16x16x32_bf16 v[70:73], v[168:171], v[228:231], v[70:73]
	v_mfma_f32_16x16x32_bf16 v[66:69], v[176:179], v[228:231], v[66:69]
	s_barrier
	s_add_u32 s38, s56, s60
	s_addc_u32 s39, s57, s61
	s_add_i32 m0, s97, 0x18000
	ds_read_b128 v[182:185], v147 offset:49152
	ds_read_b128 v[186:189], v147 offset:50176
	ds_read_b128 v[208:211], v147 offset:51200
	ds_read_b128 v[212:215], v147 offset:52224
	ds_read_b128 v[216:219], v147 offset:53248
	ds_read_b128 v[220:223], v147 offset:54272
	ds_read_b128 v[224:227], v147 offset:55296
	ds_read_b128 v[228:231], v147 offset:56320
	global_load_lds_dwordx4 v0, s[38:39]
	s_add_i32 m0, s97, 0x1a000
	s_nop 0
	global_load_lds_dwordx4 v134, s[38:39]
	s_add_u32 s38, s38, s16
	s_addc_u32 s39, s39, 0
	s_add_i32 m0, s97, 0x1c000
	global_load_lds_dwordx4 v0, s[38:39]
	s_add_i32 m0, s97, 0x1e000
	s_nop 0
	global_load_lds_dwordx4 v134, s[38:39]
	s_mov_b32 m0, s72
	s_nop 0
	global_load_lds_dwordx4 v130, s[82:83]
	s_mov_b32 m0, s73
	s_nop 0
	global_load_lds_dwordx4 v132, s[82:83]
	s_add_u32 s50, s50, s48
	s_addc_u32 s51, s51, s49
	s_cmp_ge_u32 s80, s13
	s_cselect_b64 vcc, -1, 0
	s_cbranch_scc1 .Lgemm_ctl_done
	s_cmp_eq_u32 s88, s80
	s_cbranch_scc1 .Lgemm_ctl_last
	s_add_u32 s62, s18, s50
	s_addc_u32 s63, s19, s51
	s_add_u32 s56, s87, s50
	s_addc_u32 s57, s33, s51
	s_mov_b64 s[60:61], s[44:45]
	s_branch .Lgemm_ctl_join

; #define PG8_WAIT_V(n) asm volatile("s_waitcnt vmcnt(" #n ")" ::: "memory")
; #define PG8_BAR __builtin_amdgcn_s_barrier()
; template <class Epi, class Sched, bool ALIGN_EPI = false, bool SP2 = false>
; __device__ __forceinline__ void gemm_phase(PG8_LAS unsigned char* lds, const Gemm g, const Sched& S, const Epi& E) {
;     ...
;     PG8_WAIT_V(0);
;     if constexpr (!ALIGN_EPI) { if (wr == 0) PG8_BAR; }
;     PG8_BAR;
.LBB0_373:
	s_setprio 0
	s_waitcnt vmcnt(0)
	v_readlane_b32 s70, v241, 59
	v_readlane_b32 s76, v241, 62
	v_readlane_b32 s36, v240, 7
	v_readlane_b32 s68, v241, 58
	v_readlane_b32 s71, v241, 60
	v_readlane_b32 s69, v241, 61
	v_readlane_b32 s74, v240, 9
	v_readlane_b32 s77, v241, 63
	s_movk_i32 s75, 0x1400
	s_movk_i32 s80, 0x1000
	s_mov_b32 s87, 0x8000
	s_movk_i32 s91, 0x210
	s_mov_b32 s64, 0x78000
	s_movk_i32 s65, 0x5ff
	v_readlane_b32 s37, v240, 8
	s_barrier
